# gating: LayerNorm gain/bias staged once into LDS, per-head reads from LDS instead of 8 global loads per thread
# baseline (speedup 1.0000x reference)
.LBB0_503:
	s_add_i32 s0, 0, 0x23f94
	s_waitcnt vmcnt(1)
	v_mov_b32_e32 v0, s0
	s_mov_b64 s[2:3], s[90:91]
	v_mbcnt_lo_u32_b32 v52, -1, 0
	v_mbcnt_hi_u32_b32 v52, -1, v52
	ds_read_b32 v0, v0
	s_load_dwordx2 s[70:71], s[2:3], 0x48
	s_mov_b64 s[2:3], s[90:91]
	s_load_dwordx2 s[68:69], s[2:3], 0x50
	s_mov_b64 s[2:3], s[90:91]
	s_load_dwordx2 s[72:73], s[2:3], 0x58
	s_mov_b64 s[2:3], s[90:91]
	s_waitcnt lgkmcnt(0)
	v_readfirstlane_b32 s60, v0
	s_load_dwordx2 s[62:63], s[2:3], 0x60
	s_and_b32 s0, s33, 0xffffffc0
	v_add_u32_e32 v53, s0, v52
	s_lshl_b32 s0, s60, 3
	s_and_b32 s0, s0, 56
	s_ashr_i32 s64, s60, 5
	s_add_i32 s0, s0, s64
	s_movk_i32 s2, 0x80
	s_mov_b32 s1, 0
	s_lshl_b32 s0, s0, 7
	v_cmp_gt_i32_e32 vcc, s2, v53
	s_waitcnt lgkmcnt(0)
	s_barrier
	v_add_u32_e32 v150, s0, v53
	s_and_b32 s66, s60, 7
	s_mul_i32 s2, s66, 0x1400000
	s_add_u32 s2, s94, s2
	s_addc_u32 s3, s95, 0
	s_lshl_b32 s4, s66, 23
	s_sub_u32 s4, 0, s4
	v_ashrrev_i32_e32 v60, 2, v53
	s_subb_u32 s5, 0, 0
	v_and_b32_e32 v54, -2, v60
	s_add_u32 s2, s2, s4
	v_add_u32_e32 v0, s0, v54
	s_addc_u32 s3, s3, s5
	v_ashrrev_i32_e32 v1, 31, v0
	s_lshr_b32 s0, s60, 1
	v_lshlrev_b32_e32 v58, 4, v52
	v_lshlrev_b64 v[50:51], 13, v[0:1]
	s_and_b32 s4, s0, 12
	v_and_b32_e32 v59, 0x70, v58
	v_lshl_add_u64 v[0:1], s[2:3], 0, v[50:51]
	s_lshl_b32 s0, s4, 8
	v_lshl_add_u64 v[0:1], v[0:1], 0, s[0:1]
	v_lshlrev_b32_e32 v48, 1, v59
	v_mov_b32_e32 v49, 0
	v_lshl_add_u64 v[8:9], v[0:1], 0, v[48:49]
	s_mov_b32 s0, 0x13001000
	v_add_co_u32_e32 v12, vcc, s0, v8
	s_mov_b64 s[2:3], 0x13001000
	s_nop 0
	v_addc_co_u32_e32 v13, vcc, 0, v9, vcc
	s_mov_b32 s0, 0x13003000
	v_lshl_add_u64 v[10:11], v[8:9], 0, s[2:3]
	s_mov_b64 s[2:3], 0x13003000
	v_add_co_u32_e32 v18, vcc, s0, v8
	s_lshl_b32 s0, s4, 9
	v_lshl_add_u64 v[16:17], v[8:9], 0, s[2:3]
	s_add_u32 s2, s70, s0
	s_addc_u32 s3, s71, 0
	v_addc_co_u32_e32 v19, vcc, 0, v9, vcc
	v_lshlrev_b32_e32 v48, 2, v59
	s_add_u32 s4, s68, s0
	global_load_dwordx4 v[0:3], v[12:13], off
	global_load_dwordx4 v[4:7], v[10:11], off offset:16
	s_nop 0
	global_load_dwordx4 v[8:11], v[18:19], off
	global_load_dwordx4 v[12:15], v[16:17], off offset:16
	s_addc_u32 s5, s69, 0
	v_cmp_gt_u32_e32 vcc, 0x100, v53
	v_mov_b32_e32 v222, s68
	v_mov_b32_e32 v223, s69
	v_mov_b32_e32 v224, s70
	v_mov_b32_e32 v225, s71
	v_cndmask_b32_e32 v222, v222, v224, vcc
	v_cndmask_b32_e32 v223, v223, v225, vcc
	v_and_b32_e32 v224, 0xff, v53
	v_lshlrev_b32_e32 v224, 3, v224
	v_add_u32_e32 v224, s0, v224
	v_mov_b32_e32 v225, 0
	v_lshl_add_u64 v[222:223], v[222:223], 0, v[224:225]
	global_load_dwordx2 v[220:221], v[222:223], off
	v_lshl_add_u32 v226, v53, 3, 0
	v_add_u32_e32 v226, 0x12000, v226
	v_and_b32_e32 v147, 7, v52
	v_lshl_add_u32 v147, v147, 6, 0
	v_add_u32_e32 v147, 0x12000, v147
	v_cmp_gt_i32_e32 vcc, 0x80, v53
	s_and_saveexec_b64 s[100:101], vcc
	s_cbranch_execz .Lgat_st_end
	v_ashrrev_i32_e32 v151, 31, v150
	v_lshlrev_b64 v[150:151], 8, v[150:151]
	v_lshl_add_u64 v[208:209], s[94:95], 0, v[150:151]
	s_mov_b64 s[98:99], 0x12200000
	v_add_co_u32_e32 v218, vcc, 0x12200000, v208
	v_lshl_add_u64 v[216:217], v[208:209], 0, s[98:99]
	s_nop 0
	v_addc_co_u32_e32 v219, vcc, 0, v209, vcc
	global_load_dwordx4 v[150:153], v[216:217], off offset:16
	global_load_dwordx4 v[154:157], v[216:217], off offset:32
	global_load_dwordx4 v[158:161], v[216:217], off offset:48
	global_load_dwordx4 v[162:165], v[216:217], off offset:64
	global_load_dwordx4 v[166:169], v[216:217], off offset:80
	global_load_dwordx4 v[170:173], v[216:217], off offset:96
	global_load_dwordx4 v[174:177], v[216:217], off offset:112
	global_load_dwordx4 v[178:181], v[216:217], off offset:128
	global_load_dwordx4 v[182:185], v[216:217], off offset:144
	global_load_dwordx4 v[186:189], v[216:217], off offset:160
	global_load_dwordx4 v[190:193], v[216:217], off offset:176
	global_load_dwordx4 v[194:197], v[216:217], off offset:192
	global_load_dwordx4 v[198:201], v[216:217], off offset:224
	global_load_dwordx4 v[204:207], v[216:217], off offset:208
	global_load_dwordx4 v[208:211], v[218:219], off
	global_load_dwordx4 v[212:215], v[216:217], off offset:240
	s_mov_b32 s98, 0x3a000000
	s_mov_b32 s99, 0xf800000
	s_waitcnt vmcnt(15)
	v_add_f32_e32 v150, v150, v152
	s_waitcnt vmcnt(14)
	v_add_f32_e32 v152, v154, v156
	v_add_f32_e32 v151, v151, v153
	s_waitcnt vmcnt(12)
	v_add_f32_e32 v156, v162, v164
	v_add_f32_e32 v153, v155, v157
	v_add_f32_e32 v157, v163, v165
	v_add_f32_e32 v154, v158, v160
	s_waitcnt vmcnt(8)
	v_add_f32_e32 v164, v178, v180
	v_add_f32_e32 v165, v179, v181
	v_add_f32_e32 v155, v159, v161
	v_add_f32_e32 v158, v166, v168
	s_waitcnt vmcnt(1)
	v_add_f32_e32 v178, v208, v210
	v_add_f32_e32 v178, 0, v178
	v_add_f32_e32 v179, v209, v211
	v_add_f32_e32 v150, v178, v150
	v_add_f32_e32 v179, 0, v179
	v_add_f32_e32 v150, v150, v152
	v_add_f32_e32 v151, v179, v151
	v_add_f32_e32 v150, v150, v154
	v_add_f32_e32 v151, v151, v153
	v_add_f32_e32 v150, v150, v156
	v_add_f32_e32 v160, v170, v172
	v_add_f32_e32 v151, v151, v155
	v_add_f32_e32 v150, v150, v158
	v_add_f32_e32 v159, v167, v169
	v_add_f32_e32 v162, v174, v176
	v_add_f32_e32 v151, v151, v157
	v_add_f32_e32 v150, v150, v160
	v_add_f32_e32 v161, v171, v173
	v_add_f32_e32 v151, v151, v159
	v_add_f32_e32 v150, v150, v162
	v_add_f32_e32 v163, v175, v177
	v_add_f32_e32 v166, v182, v184
	v_add_f32_e32 v151, v151, v161
	v_add_f32_e32 v150, v150, v164
	v_add_f32_e32 v168, v186, v188
	v_add_f32_e32 v151, v151, v163
	v_add_f32_e32 v150, v150, v166
	v_add_f32_e32 v167, v183, v185
	v_add_f32_e32 v170, v190, v192
	v_add_f32_e32 v151, v151, v165
	v_add_f32_e32 v150, v150, v168
	v_add_f32_e32 v169, v187, v189
	v_add_f32_e32 v172, v194, v196
	v_add_f32_e32 v151, v151, v167
	v_add_f32_e32 v150, v150, v170
	v_add_f32_e32 v171, v191, v193
	v_add_f32_e32 v174, v204, v206
	v_add_f32_e32 v151, v151, v169
	v_add_f32_e32 v150, v150, v172
	v_add_f32_e32 v173, v195, v197
	v_add_f32_e32 v176, v198, v200
	v_add_f32_e32 v151, v151, v171
	v_add_f32_e32 v150, v150, v174
	v_add_f32_e32 v175, v205, v207
	s_waitcnt vmcnt(0)
	v_add_f32_e32 v180, v212, v214
	v_add_f32_e32 v151, v151, v173
	v_add_f32_e32 v150, v150, v176
	v_add_f32_e32 v177, v199, v201
	v_add_f32_e32 v151, v151, v175
	v_add_f32_e32 v150, v150, v180
	v_add_f32_e32 v181, v213, v215
	v_add_f32_e32 v151, v151, v177
	v_mul_f32_e32 v150, 0x3a000000, v150
	v_add_f32_e32 v151, v151, v181
	v_mul_f32_e32 v152, v150, v150
	v_fma_f32 v151, v151, s98, -v152
	v_add_f32_e32 v151, 0x358637bd, v151
	v_mul_f32_e32 v152, 0x4f800000, v151
	v_cmp_gt_f32_e32 vcc, s99, v151
	v_mov_b32_e32 v154, 0x260
	v_lshl_add_u32 v153, v53, 2, 0
	v_cndmask_b32_e32 v151, v151, v152, vcc
	v_sqrt_f32_e32 v152, v151
	v_add_u32_e32 v153, 0x11000, v153
	v_add_u32_e32 v155, -1, v152
	v_add_u32_e32 v156, 1, v152
	v_fma_f32 v157, -v155, v152, v151
	v_fma_f32 v158, -v156, v152, v151
	v_cmp_ge_f32_e64 s[98:99], 0, v157
	s_nop 1
	v_cndmask_b32_e64 v152, v152, v155, s[98:99]
	v_cmp_lt_f32_e64 s[98:99], 0, v158
	s_nop 1
	v_cndmask_b32_e64 v152, v152, v156, s[98:99]
	v_mul_f32_e32 v155, 0x37800000, v152
	v_cndmask_b32_e32 v152, v152, v155, vcc
	v_cmp_class_f32_e32 vcc, v151, v154
	s_nop 1
	v_cndmask_b32_e32 v151, v152, v151, vcc
	v_div_scale_f32 v152, s[98:99], v151, v151, 1.0
	v_rcp_f32_e32 v154, v152
	v_div_scale_f32 v155, vcc, 1.0, v151, 1.0
	v_fma_f32 v156, -v152, v154, 1.0
	v_fmac_f32_e32 v154, v156, v154
	v_mul_f32_e32 v156, v155, v154
	v_fma_f32 v157, -v152, v156, v155
	v_fmac_f32_e32 v156, v157, v154
	v_fma_f32 v152, -v152, v156, v155
	v_div_fmas_f32 v152, v152, v154, v156
	v_div_fixup_f32 v151, v152, v151, 1.0
	ds_write2st64_b32 v153, v150, v151 offset1:2
.Lgat_st_end:
	s_or_b64 exec, exec, s[100:101]
	s_waitcnt vmcnt(0)
	ds_write_b64 v226, v[220:221]
	s_add_i32 s0, 0, 0x11000
	v_lshl_add_u32 v48, v54, 2, s0
	v_bitop3_b32 v53, v53, -4, 4 bitop3:0xc8
	v_ashrrev_i32_e32 v56, 4, v52
	s_waitcnt lgkmcnt(0)
	s_barrier
	ds_read_b128 v[28:31], v147
	ds_read_b128 v[24:27], v147 offset:16
	ds_read_b128 v[20:23], v147 offset:32
	ds_read_b128 v[16:19], v147 offset:48
	ds_read_b128 v[44:47], v147 offset:2048
	ds_read_b128 v[40:43], v147 offset:2064
	ds_read_b128 v[36:39], v147 offset:2080
	ds_read_b128 v[32:35], v147 offset:2096
	v_add_u32_e32 v53, s0, v53
	ds_read_b32 v124, v48
	ds_read_b64 v[92:93], v48 offset:512
	ds_read_b32 v125, v53
	v_and_b32_e32 v48, 48, v58
	v_and_b32_e32 v62, 15, v52
	s_lshl_b32 s0, s88, 4
	v_lshlrev_b32_e32 v54, 3, v56
	v_bitop3_b32 v48, v60, v48, -2 bitop3:0x6c
	v_or_b32_e32 v53, s0, v62
	v_lshlrev_b32_e32 v127, 1, v48
	v_or_b32_e32 v48, 2, v54
	v_cmp_gt_i32_e64 s[6:7], v48, v53
	v_or_b32_e32 v48, 3, v54
	v_cmp_gt_i32_e64 s[8:9], v48, v53
	v_or_b32_e32 v48, 4, v54
	v_cmp_gt_i32_e64 s[10:11], v48, v53
	v_or_b32_e32 v48, 5, v54
	v_cmp_gt_i32_e64 s[12:13], v48, v53
	v_or_b32_e32 v48, 6, v54
	v_cmp_gt_i32_e64 s[14:15], v48, v53
	v_or_b32_e32 v48, 7, v54
	v_cmp_gt_i32_e64 s[16:17], v48, v53
	v_add_u32_e32 v48, 32, v54
	v_cmp_gt_i32_e64 s[18:19], v48, v53
	v_add_u32_e32 v48, 33, v54
	v_cmp_gt_i32_e64 s[20:21], v48, v53
	v_add_u32_e32 v48, 34, v54
	v_cmp_gt_i32_e64 s[22:23], v48, v53
	v_add_u32_e32 v48, 35, v54
	v_cmp_gt_i32_e64 s[24:25], v48, v53
	v_add_u32_e32 v48, 36, v54
	v_cmp_gt_i32_e64 s[26:27], v48, v53
	v_add_u32_e32 v48, 37, v54
	v_cmp_gt_i32_e64 s[28:29], v48, v53
	v_add_u32_e32 v48, 38, v54
	v_cmp_gt_i32_e64 s[30:31], v48, v53
	v_add_u32_e32 v48, 39, v54
	v_cmp_gt_i32_e64 s[34:35], v48, v53
	v_add_u32_e32 v48, 64, v54
	v_cmp_gt_i32_e64 s[36:37], v48, v53
	v_add_u32_e32 v48, 0x41, v54
	v_cmp_gt_i32_e64 s[38:39], v48, v53
	v_add_u32_e32 v48, 0x42, v54
	v_cmp_gt_i32_e64 s[40:41], v48, v53
	v_add_u32_e32 v48, 0x43, v54
	v_cmp_gt_i32_e64 s[42:43], v48, v53
	v_add_u32_e32 v48, 0x44, v54
	v_cmp_gt_i32_e64 s[44:45], v48, v53
	v_add_u32_e32 v48, 0x45, v54
	s_cmpk_gt_u32 s33, 0x7f
	v_cmp_gt_i32_e64 s[46:47], v48, v53
	v_add_u32_e32 v48, 0x46, v54
	s_cselect_b64 s[76:77], -1, 0
	s_cmpk_gt_u32 s33, 0xff
	v_cmp_gt_i32_e64 s[48:49], v48, v53
	v_add_u32_e32 v48, 0x47, v54
	s_cselect_b64 s[78:79], -1, 0
	s_cmpk_gt_u32 s33, 0x17f
	v_cmp_gt_i32_e64 s[50:51], v48, v53
	v_add_u32_e32 v48, 0x60, v54
	s_cselect_b64 s[80:81], -1, 0
	v_cmp_gt_i32_e64 s[52:53], v48, v53
	v_add_u32_e32 v48, 0x61, v54
	s_bfe_u32 s82, s60, 0x20003
	v_cmp_gt_i32_e64 s[54:55], v48, v53
	v_add_u32_e32 v48, 0x62, v54
	s_lshl_b32 s60, s82, 9
	v_cmp_gt_i32_e64 s[56:57], v48, v53
	v_add_u32_e32 v48, 0x63, v54
	s_add_i32 s60, s60, s0
	v_cmp_gt_i32_e64 s[58:59], v48, v53
	v_or_b32_e32 v48, s60, v62
	v_lshl_add_u64 v[94:95], v[48:49], 2, s[62:63]
	s_lshl_b32 s62, s66, 10
	s_lshl_b32 s63, s64, 7
	v_add_u32_e32 v58, 0x64, v54
	s_add_i32 s64, s62, s63
	v_cmp_gt_i32_e64 s[60:61], v58, v53
	v_add_u32_e32 v58, 0x65, v54
	s_add_i32 s64, s64, s0
	v_cmp_gt_i32_e64 s[62:63], v58, v53
	v_or_b32_e32 v58, s64, v62
	v_lshlrev_b32_e32 v56, 2, v56
	v_mul_u32_u24_e32 v126, 0x110, v59
	v_ashrrev_i32_e32 v59, 31, v58
	v_ashrrev_i32_e32 v57, 31, v56
	s_lshl_b32 s64, s66, 24
	s_mov_b32 s65, s1
	v_lshlrev_b64 v[60:61], 12, v[58:59]
	v_lshl_add_u64 v[60:61], s[64:65], 0, v[60:61]
	v_lshlrev_b64 v[56:57], 1, v[56:57]
	v_lshl_add_u64 v[60:61], v[60:61], 0, v[56:57]
	v_lshl_add_u64 v[60:61], s[94:95], 0, v[60:61]
	s_mov_b64 s[64:65], 0x13800080
	s_movk_i32 s67, 0x60
	v_lshl_add_u64 v[96:97], v[60:61], 0, s[64:65]
	v_lshlrev_b64 v[58:59], 13, v[58:59]
	v_mov_b32_e32 v60, 0xc00000
	v_mad_u64_u32 v[58:59], s[64:65], s66, v60, v[58:59]
	v_bitop3_b32 v128, v52, s67, -16 bitop3:0x6c
	v_mad_u64_u32 v[50:51], s[66:67], s66, v60, v[50:51]
	v_and_b32_e32 v130, -16, v52
	v_bitop3_b32 v131, v52, 32, -16 bitop3:0x6c
	v_bitop3_b32 v132, v52, 64, -16 bitop3:0x6c
	v_and_b32_e32 v52, 7, v52
	v_lshl_add_u64 v[56:57], v[58:59], 0, v[56:57]
	v_lshl_or_b32 v50, v52, 5, v50
	v_ashrrev_i32_e32 v55, 31, v54
	v_lshl_add_u64 v[56:57], s[94:95], 0, v[56:57]
	s_mov_b64 s[64:65], 0x13000080
	v_lshl_add_u64 v[100:101], s[94:95], 0, v[50:51]
	v_mov_b32_e32 v51, v49
	v_lshlrev_b64 v[48:49], 9, v[48:49]
	v_add_u32_e32 v63, 0x66, v54
	v_lshl_add_u64 v[98:99], v[56:57], 0, s[64:65]
	v_add_u32_e32 v56, 0x67, v54
	v_lshlrev_b32_e32 v50, 6, v52
	v_lshl_add_u64 v[48:49], v[54:55], 2, v[48:49]
	v_cmp_gt_i32_e64 s[2:3], v54, v53
	v_cmp_lt_i32_e64 s[4:5], v54, v53
	v_cmp_gt_i32_e64 s[64:65], v63, v53
	v_cmp_gt_i32_e64 s[66:67], v56, v53
	v_add_u32_e32 v53, 64, v130
	v_add_u32_e32 v56, 0xc0, v130
	s_lshl_b32 s0, s82, 10
	v_lshl_or_b32 v50, s82, 11, v50
	v_lshl_add_u64 v[48:49], s[72:73], 0, v[48:49]
	s_mov_b64 s[82:83], 0x100
	s_mov_b64 s[74:75], 0
	s_mov_b32 s96, s88
	v_mul_u32_u24_e32 v129, 0x110, v62
	v_xor_b32_e32 v133, 64, v53
	v_xor_b32_e32 v134, 64, v56
	v_xor_b32_e32 v135, 0x60, v53
	v_xor_b32_e32 v136, 0x60, v56
	v_lshl_add_u64 v[102:103], s[70:71], 0, v[50:51]
	v_lshl_add_u64 v[104:105], v[48:49], 0, s[82:83]
	v_lshl_add_u64 v[106:107], s[68:69], 0, v[50:51]
	s_mov_b32 s84, 0xffff0000
	s_movk_i32 s85, 0x7fff
	s_mov_b32 s88, s1
	v_lshl_add_u64 v[76:77], v[94:95], 0, s[74:75]
	global_load_dword v137, v[76:77], off
	v_lshl_add_u64 v[76:77], v[98:99], 0, s[0:1]
	global_load_dwordx2 v[122:123], v[76:77], off offset:-128
	global_load_dwordx2 v[120:121], v[76:77], off offset:-96
	global_load_dwordx2 v[118:119], v[76:77], off offset:-64
	global_load_dwordx2 v[116:117], v[76:77], off offset:-32
	global_load_dwordx2 v[114:115], v[76:77], off
	global_load_dwordx2 v[112:113], v[76:77], off offset:32
	global_load_dwordx2 v[110:111], v[76:77], off offset:64
	global_load_dwordx2 v[108:109], v[76:77], off offset:96
	v_mbcnt_lo_u32_b32 v148, -1, 0
	v_mbcnt_hi_u32_b32 v148, -1, v148
	v_lshrrev_b32_e32 v148, 4, v148
	v_and_b32_e32 v148, 1, v148
	v_mul_u32_u24_e32 v148, 24, v148
	v_mov_b32_e32 v149, 0
	s_waitcnt vmcnt(9)
	s_branch .Lgat_top2

.LBB0_511:
	s_cmp_lg_u32 s74, 0x600
	s_cselect_b32 s98, 0x200, 0
	s_cselect_b32 s100, s82, 0
	s_cselect_b32 s101, s83, 0
	s_add_u32 s98, s74, s98
	s_addc_u32 s99, s75, 0
	v_lshl_add_u64 v[76:77], v[94:95], 0, s[98:99]
	global_load_dword v208, v[76:77], off
	v_lshl_add_u64 v[76:77], v[98:99], 0, s[0:1]
	v_lshl_add_u64 v[76:77], v[76:77], 0, s[100:101]
	v_lshl_add_u64 v[76:77], v[76:77], 0, v[148:149]
	global_load_dwordx4 v[192:195], v[76:77], off offset:-128
	global_load_dwordx4 v[196:199], v[76:77], off offset:-64
	global_load_dwordx4 v[200:203], v[76:77], off
	global_load_dwordx4 v[204:207], v[76:77], off offset:64
	s_waitcnt vmcnt(22)
	v_lshlrev_b32_e32 v77, 16, v0
	s_bitcmp1_b32 s88, 0
	s_waitcnt lgkmcnt(2)
	v_sub_f32_e32 v77, v77, v124
	s_waitcnt vmcnt(20)
	v_lshlrev_b32_e32 v78, 16, v8
	s_cselect_b32 s89, 0x8800, 0
	s_waitcnt lgkmcnt(1)
	v_mul_f32_e32 v77, v92, v77
	s_waitcnt lgkmcnt(0)
	v_sub_f32_e32 v78, v78, v125
	s_add_i32 s89, s89, 0
	s_waitcnt vmcnt(11)
	v_fma_f32 v77, v28, v77, v44
	v_mul_f32_e32 v78, v93, v78
	v_add3_u32 v76, s89, v126, v127
	v_fma_f32 v78, v28, v78, v44
	v_cvt_pk_bf16_f32 v77, v77, v78
	ds_write_b32 v76, v77
	v_and_b32_e32 v77, 0xffff0000, v0
	v_sub_f32_e32 v77, v77, v124
	v_and_b32_e32 v78, 0xffff0000, v8
	v_mul_f32_e32 v77, v92, v77
	v_sub_f32_e32 v78, v78, v125
	v_fma_f32 v77, v29, v77, v45
	v_mul_f32_e32 v78, v93, v78
	v_fma_f32 v78, v29, v78, v45
	v_cvt_pk_bf16_f32 v77, v77, v78
	ds_write_b32 v76, v77 offset:272
	v_lshlrev_b32_e32 v77, 16, v1
	v_sub_f32_e32 v77, v77, v124
	v_lshlrev_b32_e32 v78, 16, v9
	v_mul_f32_e32 v77, v92, v77
	v_sub_f32_e32 v78, v78, v125
	v_fma_f32 v77, v30, v77, v46
	v_mul_f32_e32 v78, v93, v78
	v_fma_f32 v78, v30, v78, v46
	v_cvt_pk_bf16_f32 v77, v77, v78
	ds_write_b32 v76, v77 offset:544
	v_and_b32_e32 v77, 0xffff0000, v1
	v_sub_f32_e32 v77, v77, v124
	v_and_b32_e32 v78, 0xffff0000, v9
	v_mul_f32_e32 v77, v92, v77
	v_sub_f32_e32 v78, v78, v125
	v_fma_f32 v77, v31, v77, v47
	v_mul_f32_e32 v78, v93, v78
	v_fma_f32 v78, v31, v78, v47
	v_cvt_pk_bf16_f32 v77, v77, v78
	ds_write_b32 v76, v77 offset:816
	v_lshlrev_b32_e32 v77, 16, v2
	v_sub_f32_e32 v77, v77, v124
	v_lshlrev_b32_e32 v78, 16, v10
	v_mul_f32_e32 v77, v92, v77
	v_sub_f32_e32 v78, v78, v125
	v_fma_f32 v77, v24, v77, v40
	v_mul_f32_e32 v78, v93, v78
	v_fma_f32 v78, v24, v78, v40
	v_cvt_pk_bf16_f32 v77, v77, v78
	ds_write_b32 v76, v77 offset:1088
	v_and_b32_e32 v77, 0xffff0000, v2
	v_sub_f32_e32 v77, v77, v124
	v_and_b32_e32 v78, 0xffff0000, v10
	v_mul_f32_e32 v77, v92, v77
	v_sub_f32_e32 v78, v78, v125
	v_fma_f32 v77, v25, v77, v41
	v_mul_f32_e32 v78, v93, v78
	v_fma_f32 v78, v25, v78, v41
	v_cvt_pk_bf16_f32 v77, v77, v78
	ds_write_b32 v76, v77 offset:1360
	v_lshlrev_b32_e32 v77, 16, v3
	v_sub_f32_e32 v77, v77, v124
	v_lshlrev_b32_e32 v78, 16, v11
	v_mul_f32_e32 v77, v92, v77
	v_sub_f32_e32 v78, v78, v125
	v_fma_f32 v77, v26, v77, v42
	v_mul_f32_e32 v78, v93, v78
	v_fma_f32 v78, v26, v78, v42
	v_cvt_pk_bf16_f32 v77, v77, v78
	ds_write_b32 v76, v77 offset:1632
	v_and_b32_e32 v77, 0xffff0000, v3
	v_sub_f32_e32 v77, v77, v124
	v_and_b32_e32 v78, 0xffff0000, v11
	v_mul_f32_e32 v77, v92, v77
	v_sub_f32_e32 v78, v78, v125
	v_fma_f32 v77, v27, v77, v43
	v_mul_f32_e32 v78, v93, v78
	v_fma_f32 v78, v27, v78, v43
	v_cvt_pk_bf16_f32 v77, v77, v78
	ds_write_b32 v76, v77 offset:1904
	v_lshlrev_b32_e32 v77, 16, v4
	v_sub_f32_e32 v77, v77, v124
	v_lshlrev_b32_e32 v78, 16, v12
	v_mul_f32_e32 v77, v92, v77
	v_sub_f32_e32 v78, v78, v125
	v_fma_f32 v77, v20, v77, v36
	v_mul_f32_e32 v78, v93, v78
	v_fma_f32 v78, v20, v78, v36
	v_cvt_pk_bf16_f32 v77, v77, v78
	ds_write_b32 v76, v77 offset:2176
	v_and_b32_e32 v77, 0xffff0000, v4
	v_sub_f32_e32 v77, v77, v124
	v_and_b32_e32 v78, 0xffff0000, v12
	v_mul_f32_e32 v77, v92, v77
	v_sub_f32_e32 v78, v78, v125
	v_fma_f32 v77, v21, v77, v37
	v_mul_f32_e32 v78, v93, v78
	v_fma_f32 v78, v21, v78, v37
	v_cvt_pk_bf16_f32 v77, v77, v78
	ds_write_b32 v76, v77 offset:2448
	v_lshlrev_b32_e32 v77, 16, v5
	v_sub_f32_e32 v77, v77, v124
	v_lshlrev_b32_e32 v78, 16, v13
	v_mul_f32_e32 v77, v92, v77
	v_sub_f32_e32 v78, v78, v125
	v_fma_f32 v77, v22, v77, v38
	v_mul_f32_e32 v78, v93, v78
	v_fma_f32 v78, v22, v78, v38
	v_cvt_pk_bf16_f32 v77, v77, v78
	ds_write_b32 v76, v77 offset:2720
	v_and_b32_e32 v77, 0xffff0000, v5
	v_sub_f32_e32 v77, v77, v124
	v_and_b32_e32 v78, 0xffff0000, v13
	v_mul_f32_e32 v77, v92, v77
	v_sub_f32_e32 v78, v78, v125
	v_fma_f32 v77, v23, v77, v39
	v_mul_f32_e32 v78, v93, v78
	v_fma_f32 v78, v23, v78, v39
	v_cvt_pk_bf16_f32 v77, v77, v78
	ds_write_b32 v76, v77 offset:2992
	v_lshlrev_b32_e32 v77, 16, v6
	v_sub_f32_e32 v77, v77, v124
	v_lshlrev_b32_e32 v78, 16, v14
	v_mul_f32_e32 v77, v92, v77
	v_sub_f32_e32 v78, v78, v125
	v_fma_f32 v77, v16, v77, v32
	v_mul_f32_e32 v78, v93, v78
	v_fma_f32 v78, v16, v78, v32
	v_cvt_pk_bf16_f32 v77, v77, v78
	ds_write_b32 v76, v77 offset:3264
	v_and_b32_e32 v77, 0xffff0000, v6
	v_sub_f32_e32 v77, v77, v124
	v_and_b32_e32 v78, 0xffff0000, v14
	v_mul_f32_e32 v77, v92, v77
	v_sub_f32_e32 v78, v78, v125
	v_fma_f32 v77, v17, v77, v33
	v_mul_f32_e32 v78, v93, v78
	v_fma_f32 v78, v17, v78, v33
	v_cvt_pk_bf16_f32 v77, v77, v78
	ds_write_b32 v76, v77 offset:3536
	v_lshlrev_b32_e32 v77, 16, v7
	v_sub_f32_e32 v77, v77, v124
	v_lshlrev_b32_e32 v78, 16, v15
	v_mul_f32_e32 v77, v92, v77
	v_sub_f32_e32 v78, v78, v125
	v_fma_f32 v77, v18, v77, v34
	v_mul_f32_e32 v78, v93, v78
	v_fma_f32 v78, v18, v78, v34
	v_cvt_pk_bf16_f32 v77, v77, v78
	ds_write_b32 v76, v77 offset:3808
	v_and_b32_e32 v77, 0xffff0000, v7
	v_sub_f32_e32 v77, v77, v124
	v_and_b32_e32 v78, 0xffff0000, v15
	v_mul_f32_e32 v77, v92, v77
	v_sub_f32_e32 v78, v78, v125
	v_fma_f32 v77, v19, v77, v35
	v_mul_f32_e32 v78, v93, v78
	s_cmpk_eq_i32 s74, 0x600
	v_fma_f32 v78, v19, v78, v35
	v_cvt_pk_bf16_f32 v77, v77, v78
	ds_write_b32 v76, v77 offset:4080
	s_cbranch_scc1 .LBB0_513
	v_lshl_add_u64 v[8:9], v[100:101], 0, s[0:1]
	s_mov_b64 s[90:91], 0x13001100
	v_add_co_u32_e32 v0, vcc, 0x13001000, v8
	v_lshl_add_u64 v[4:5], v[8:9], 0, s[90:91]
	s_nop 0
	v_addc_co_u32_e32 v1, vcc, 0, v9, vcc
	s_mov_b64 s[90:91], 0x13003100
	v_lshl_add_u64 v[12:13], v[8:9], 0, s[90:91]
	v_add_co_u32_e32 v8, vcc, 0x13003000, v8
	s_nop 0
	v_addc_co_u32_e32 v9, vcc, 0, v9, vcc
	global_load_dwordx4 v[0:3], v[0:1], off offset:256
	s_nop 0
	global_load_dwordx4 v[4:7], v[4:5], off offset:16
	s_nop 0
	global_load_dwordx4 v[8:11], v[8:9], off offset:256
	s_nop 0
	global_load_dwordx4 v[12:15], v[12:13], off offset:16
	s_nop 0
	s_add_i32 s98, s88, 1
	s_lshl_b32 s98, s98, 9
	v_add_u32_e32 v146, s98, v147
	ds_read_b128 v[28:31], v146
	ds_read_b128 v[24:27], v146 offset:16
	ds_read_b128 v[20:23], v146 offset:32
	ds_read_b128 v[16:19], v146 offset:48
	ds_read_b128 v[44:47], v146 offset:2048
	ds_read_b128 v[40:43], v146 offset:2064
	ds_read_b128 v[36:39], v146 offset:2080
	ds_read_b128 v[32:35], v146 offset:2096
	v_readlane_b32 s90, v252, 6
	v_readlane_b32 s91, v252, 7
